# attention output store tail widened: lane pairs L/L+32 exchange 8-byte pieces via v_permlane32_swap, 4 x dwordx4 stores per lane instead of 8 x dwordx2
# speedup vs baseline: 1.0005x; 1.0005x over previous
; __device__ __forceinline__ unsigned pk2(float lo, float hi) { const f32x2cv v = {lo, hi}; return __builtin_bit_cast(unsigned, __builtin_convertvector(v, bf16x2cv)); }
; __device__ __forceinline__ void attn_item_mfma(Frame& F, const Args& AR, int l, int item) {
;     ...
;     {
;         const float lt = lsum + __shfl_xor(lsum, 32), inv = 1.0f / lt;
;         bf16* op = CAT + (size_t)qrow * DM + h * 64;
; #pragma unroll
;         for (int db = 0; db < 2; ++db)
; #pragma unroll
;             for (int rq = 0; rq < 4; ++rq) { v2u w; w.x = pk2(o[db][4 * rq] * inv, o[db][4 * rq + 1] * inv); w.y = pk2(o[db][4 * rq + 2] * inv, o[db][4 * rq + 3] * inv);
;                 *(v2u*)(op + 32 * db + 8 * rq + 4 * hi) = w; }
;     }
.LBB0_1305:
	ds_bpermute_b32 v35, v107, v34
	v_readlane_b32 s0, v250, 52
	v_lshlrev_b64 v[36:37], 12, v[94:95]
	v_readlane_b32 s1, v250, 53
	v_lshlrev_b32_e32 v194, 3, v103
	s_waitcnt lgkmcnt(0)
	v_add_f32_e32 v38, v34, v35
	v_lshl_add_u64 v[36:37], s[0:1], 0, v[36:37]
	v_div_scale_f32 v39, s[0:1], v38, v38, 1.0
	v_rcp_f32_e32 v40, v39
	v_readlane_b32 s0, v254, 55
	v_readlane_b32 s1, v254, 56
	v_readlane_b32 s64, v250, 18
	v_readlane_b32 s72, v250, 26
	v_lshl_add_u64 v[34:35], s[0:1], 1, v[36:37]
	v_fma_f32 v37, -v39, v40, 1.0
	v_div_scale_f32 v36, vcc, 1.0, v38, 1.0
	v_fmac_f32_e32 v40, v37, v40
	v_mul_f32_e32 v37, v36, v40
	v_fma_f32 v41, -v39, v37, v36
	v_fmac_f32_e32 v37, v41, v40
	v_fma_f32 v36, -v39, v37, v36
	v_div_fmas_f32 v36, v36, v40, v37
	v_div_fixup_f32 v36, v36, v38, 1.0
	v_readlane_b32 s73, v250, 27
	v_readlane_b32 s74, v250, 28
	v_readlane_b32 s75, v250, 29
	v_readlane_b32 s78, v250, 32
	v_readlane_b32 s79, v250, 33
	v_readlane_b32 s84, v254, 19
	v_readlane_b32 s82, v254, 27
	v_readlane_b32 s76, v250, 30
	v_readlane_b32 s77, v250, 31
	v_readlane_b32 s92, v250, 50
	v_readlane_b32 s94, v254, 29
	v_readlane_b32 s96, v254, 31
	v_readlane_b32 s72, v254, 33
	v_readlane_b32 s74, v254, 35
	v_readlane_b32 s78, v254, 37
	v_readlane_b32 s34, v254, 40
	v_readlane_b32 s80, v254, 18
	v_readlane_b32 s85, v254, 20
	v_readlane_b32 s86, v254, 21
	v_readlane_b32 s87, v254, 22
	v_readlane_b32 s88, v254, 23
	v_readlane_b32 s89, v254, 24
	v_readlane_b32 s90, v254, 25
	v_readlane_b32 s91, v254, 26
	v_readlane_b32 s83, v254, 28
	v_readlane_b32 s65, v250, 19
	v_readlane_b32 s66, v250, 20
	v_readlane_b32 s67, v250, 21
	v_readlane_b32 s68, v250, 22
	v_readlane_b32 s69, v250, 23
	v_readlane_b32 s70, v250, 24
	v_readlane_b32 s71, v250, 25
	v_readlane_b32 s93, v250, 51
	v_readlane_b32 s81, v254, 54
	v_readlane_b32 s95, v254, 30
	v_readlane_b32 s97, v254, 32
	v_readlane_b32 s73, v254, 34
	v_readlane_b32 s75, v254, 36
	s_movk_i32 s76, 0xbc
	v_readlane_b32 s79, v254, 38
	v_readlane_b32 s77, v254, 39
	v_readlane_b32 s35, v254, 41
	s_movk_i32 s25, 0x1600
	s_movk_i32 s24, 0x410
	v_readlane_b32 s14, v254, 14
	v_lshl_add_u64 v[34:35], v[34:35], 0, v[194:195]
	v_pk_mul_f32 v[18:19], v[18:19], v[36:37] op_sel_hi:[1,0]
	v_pk_mul_f32 v[20:21], v[20:21], v[36:37] op_sel_hi:[1,0]
	v_pk_mul_f32 v[22:23], v[22:23], v[36:37] op_sel_hi:[1,0]
	v_pk_mul_f32 v[24:25], v[24:25], v[36:37] op_sel_hi:[1,0]
	v_pk_mul_f32 v[26:27], v[26:27], v[36:37] op_sel_hi:[1,0]
	v_pk_mul_f32 v[28:29], v[28:29], v[36:37] op_sel_hi:[1,0]
	v_pk_mul_f32 v[30:31], v[30:31], v[36:37] op_sel_hi:[1,0]
	v_pk_mul_f32 v[32:33], v[32:33], v[36:37] op_sel_hi:[1,0]
	v_pk_mul_f32 v[2:3], v[2:3], v[36:37] op_sel_hi:[1,0]
	v_pk_mul_f32 v[4:5], v[4:5], v[36:37] op_sel_hi:[1,0]
	v_pk_mul_f32 v[6:7], v[6:7], v[36:37] op_sel_hi:[1,0]
	v_pk_mul_f32 v[8:9], v[8:9], v[36:37] op_sel_hi:[1,0]
	v_pk_mul_f32 v[10:11], v[10:11], v[36:37] op_sel_hi:[1,0]
	v_pk_mul_f32 v[12:13], v[12:13], v[36:37] op_sel_hi:[1,0]
	v_pk_mul_f32 v[14:15], v[14:15], v[36:37] op_sel_hi:[1,0]
	v_pk_mul_f32 v[16:17], v[16:17], v[36:37] op_sel_hi:[1,0]
	v_cvt_pk_bf16_f32 v200, v18, v19
	v_cvt_pk_bf16_f32 v201, v20, v21
	v_cvt_pk_bf16_f32 v204, v22, v23
	v_cvt_pk_bf16_f32 v205, v24, v25
	v_cvt_pk_bf16_f32 v202, v26, v27
	v_cvt_pk_bf16_f32 v203, v28, v29
	v_cvt_pk_bf16_f32 v206, v30, v31
	v_cvt_pk_bf16_f32 v207, v32, v33
	v_cvt_pk_bf16_f32 v208, v2, v3
	v_cvt_pk_bf16_f32 v209, v4, v5
	v_cvt_pk_bf16_f32 v212, v6, v7
	v_cvt_pk_bf16_f32 v213, v8, v9
	v_cvt_pk_bf16_f32 v210, v10, v11
	v_cvt_pk_bf16_f32 v211, v12, v13
	v_cvt_pk_bf16_f32 v214, v14, v15
	v_cvt_pk_bf16_f32 v215, v16, v17
	s_nop 1
	v_permlane32_swap_b32_e32 v200, v202
	v_permlane32_swap_b32_e32 v201, v203
	v_permlane32_swap_b32_e32 v204, v206
	v_permlane32_swap_b32_e32 v205, v207
	v_permlane32_swap_b32_e32 v208, v210
	v_permlane32_swap_b32_e32 v209, v211
	v_permlane32_swap_b32_e32 v212, v214
	v_permlane32_swap_b32_e32 v213, v215
	global_store_dwordx4 v[34:35], v[200:203], off
	global_store_dwordx4 v[34:35], v[204:207], off offset:16
	global_store_dwordx4 v[34:35], v[208:211], off offset:64
	global_store_dwordx4 v[34:35], v[212:215], off offset:80
	s_and_saveexec_b64 s[0:1], s[92:93]
	s_cbranch_execnz .LBB0_1517
	s_branch .LBB0_1518
